# gate/up and w_in unit loops: accumulators zeroed with 64 v_mov_b64 instead of 128 v_mov_b32; gate/up LDS-DMA wait taken after the zero-init
# speedup vs baseline: 1.0063x; 1.0063x over previous
; template <class Epi, class Sched>
; DI void gemm_phase(LAS unsigned char* lds, const Gemm g, const Sched& S, const Epi& E) {
;     ...
;     if (!has_next) break;
; #pragma unroll
;     for (int a = 0; a < 2; ++a)
; #pragma unroll
;       for (int b = 0; b < 2; ++b)
; #pragma unroll
;         for (int m = 0; m < 4; ++m)
; #pragma unroll
;           for (int n = 0; n < 2; ++n) acc[a][b][m][n] = (f32x4){0.f, 0.f, 0.f, 0.f};
;     cur = nxt; cA = nA; cB = nB; ++ui;
.LBB0_176:
	v_mov_b64_e32 v[2:3], 0
	s_andn2_b64 vcc, exec, s[16:17]
	v_mov_b64_e32 v[4:5], 0
	v_mov_b64_e32 v[6:7], 0
	v_mov_b64_e32 v[8:9], 0
	v_mov_b64_e32 v[10:11], 0
	v_mov_b64_e32 v[12:13], 0
	v_mov_b64_e32 v[14:15], 0
	v_mov_b64_e32 v[16:17], 0
	v_mov_b64_e32 v[18:19], 0
	v_mov_b64_e32 v[20:21], 0
	v_mov_b64_e32 v[22:23], 0
	v_mov_b64_e32 v[24:25], 0
	v_mov_b64_e32 v[26:27], 0
	v_mov_b64_e32 v[28:29], 0
	v_mov_b64_e32 v[30:31], 0
	v_mov_b64_e32 v[32:33], 0
	v_mov_b64_e32 v[34:35], 0
	v_mov_b64_e32 v[36:37], 0
	v_mov_b64_e32 v[38:39], 0
	v_mov_b64_e32 v[40:41], 0
	v_mov_b64_e32 v[42:43], 0
	v_mov_b64_e32 v[44:45], 0
	v_mov_b64_e32 v[46:47], 0
	v_mov_b64_e32 v[48:49], 0
	v_mov_b64_e32 v[50:51], 0
	v_mov_b64_e32 v[52:53], 0
	v_mov_b64_e32 v[54:55], 0
	v_mov_b64_e32 v[56:57], 0
	v_mov_b64_e32 v[58:59], 0
	v_mov_b64_e32 v[60:61], 0
	v_mov_b64_e32 v[62:63], 0
	v_mov_b64_e32 v[64:65], 0
	v_mov_b64_e32 v[66:67], 0
	v_mov_b64_e32 v[68:69], 0
	v_mov_b64_e32 v[70:71], 0
	v_mov_b64_e32 v[72:73], 0
	v_mov_b64_e32 v[74:75], 0
	v_mov_b64_e32 v[76:77], 0
	v_mov_b64_e32 v[78:79], 0
	v_mov_b64_e32 v[80:81], 0
	v_mov_b64_e32 v[82:83], 0
	v_mov_b64_e32 v[84:85], 0
	v_mov_b64_e32 v[86:87], 0
	v_mov_b64_e32 v[88:89], 0
	v_mov_b64_e32 v[90:91], 0
	v_mov_b64_e32 v[92:93], 0
	v_mov_b64_e32 v[94:95], 0
	v_mov_b64_e32 v[96:97], 0
	v_mov_b64_e32 v[98:99], 0
	v_mov_b64_e32 v[100:101], 0
	v_mov_b64_e32 v[102:103], 0
	v_mov_b64_e32 v[104:105], 0
	v_mov_b64_e32 v[106:107], 0
	v_mov_b64_e32 v[108:109], 0
	v_mov_b64_e32 v[110:111], 0
	v_mov_b64_e32 v[112:113], 0
	v_mov_b64_e32 v[114:115], 0
	v_mov_b64_e32 v[116:117], 0
	v_mov_b64_e32 v[118:119], 0
	v_mov_b64_e32 v[120:121], 0
	v_mov_b64_e32 v[122:123], 0
	v_mov_b64_e32 v[124:125], 0
	v_mov_b64_e32 v[126:127], 0
	v_mov_b64_e32 v[128:129], 0
	s_waitcnt vmcnt(8)
	s_cbranch_vccnz .LBB0_162
	s_add_u32 s22, s22, 0x80
	s_addc_u32 s23, s23, 0
	s_add_u32 s49, s24, 0x100
	s_addc_u32 s50, s25, 0
	s_mov_b32 s24, 0
	.p2align	6

; template <class Epi, class Sched>
; DI void gemm_phase(LAS unsigned char* lds, const Gemm g, const Sched& S, const Epi& E) {
;     ...
;     if (!has_next) break;
; #pragma unroll
;     for (int a = 0; a < 2; ++a)
; #pragma unroll
;       for (int b = 0; b < 2; ++b)
; #pragma unroll
;         for (int m = 0; m < 4; ++m)
; #pragma unroll
;           for (int n = 0; n < 2; ++n) acc[a][b][m][n] = (f32x4){0.f, 0.f, 0.f, 0.f};
;     cur = nxt; cA = nA; cB = nB; ++ui;
.LBB0_517:
	v_mov_b64_e32 v[2:3], 0
	s_andn2_b64 vcc, exec, s[18:19]
	s_waitcnt vmcnt(0)
	v_mov_b64_e32 v[4:5], 0
	v_mov_b64_e32 v[6:7], 0
	v_mov_b64_e32 v[8:9], 0
	v_mov_b64_e32 v[10:11], 0
	v_mov_b64_e32 v[12:13], 0
	v_mov_b64_e32 v[14:15], 0
	v_mov_b64_e32 v[16:17], 0
	v_mov_b64_e32 v[18:19], 0
	v_mov_b64_e32 v[20:21], 0
	v_mov_b64_e32 v[22:23], 0
	v_mov_b64_e32 v[24:25], 0
	v_mov_b64_e32 v[26:27], 0
	v_mov_b64_e32 v[28:29], 0
	v_mov_b64_e32 v[30:31], 0
	v_mov_b64_e32 v[32:33], 0
	v_mov_b64_e32 v[34:35], 0
	v_mov_b64_e32 v[36:37], 0
	v_mov_b64_e32 v[38:39], 0
	v_mov_b64_e32 v[40:41], 0
	v_mov_b64_e32 v[42:43], 0
	v_mov_b64_e32 v[44:45], 0
	v_mov_b64_e32 v[46:47], 0
	v_mov_b64_e32 v[48:49], 0
	v_mov_b64_e32 v[50:51], 0
	v_mov_b64_e32 v[52:53], 0
	v_mov_b64_e32 v[54:55], 0
	v_mov_b64_e32 v[56:57], 0
	v_mov_b64_e32 v[58:59], 0
	v_mov_b64_e32 v[60:61], 0
	v_mov_b64_e32 v[62:63], 0
	v_mov_b64_e32 v[64:65], 0
	v_mov_b64_e32 v[90:91], 0
	v_mov_b64_e32 v[92:93], 0
	v_mov_b64_e32 v[102:103], 0
	v_mov_b64_e32 v[104:105], 0
	v_mov_b64_e32 v[106:107], 0
	v_mov_b64_e32 v[108:109], 0
	v_mov_b64_e32 v[110:111], 0
	v_mov_b64_e32 v[112:113], 0
	v_mov_b64_e32 v[130:131], 0
	v_mov_b64_e32 v[132:133], 0
	v_mov_b64_e32 v[134:135], 0
	v_mov_b64_e32 v[136:137], 0
	v_mov_b64_e32 v[138:139], 0
	v_mov_b64_e32 v[140:141], 0
	v_mov_b64_e32 v[142:143], 0
	v_mov_b64_e32 v[144:145], 0
	v_mov_b64_e32 v[146:147], 0
	v_mov_b64_e32 v[148:149], 0
	v_mov_b64_e32 v[150:151], 0
	v_mov_b64_e32 v[152:153], 0
	v_mov_b64_e32 v[154:155], 0
	v_mov_b64_e32 v[156:157], 0
	v_mov_b64_e32 v[158:159], 0
	v_mov_b64_e32 v[160:161], 0
	v_mov_b64_e32 v[162:163], 0
	v_mov_b64_e32 v[164:165], 0
	v_mov_b64_e32 v[166:167], 0
	v_mov_b64_e32 v[168:169], 0
	v_mov_b64_e32 v[170:171], 0
	v_mov_b64_e32 v[172:173], 0
	v_mov_b64_e32 v[174:175], 0
	v_mov_b64_e32 v[176:177], 0
	s_cbranch_vccnz .LBB0_521
	s_add_u32 s2, s2, 0x80
	s_addc_u32 s3, s3, 0
	s_add_u32 s11, s8, 0x100
	v_mov_b32_e32 v200, v184
	v_mov_b32_e32 v201, 0x358637bd
	v_mov_b32_e32 v210, 0x3e38aa3b
	v_mov_b32_e32 v217, 1
	v_mov_b64_e32 v[178:179], 0x200
	s_addc_u32 s22, s9, 0
	s_mov_b32 s6, 0
	.p2align	6
